# differential-attention lambda computed once per layer per workgroup (cached in spare lanes) instead of per item; item prologue no longer waits on the lambda loads and reduction before issuing the Q lo
# speedup vs baseline: 1.0112x; 1.0002x over previous
.LBB0_479:
	s_or_b64 exec, exec, s[10:11]
	v_mov_b32_e32 v235, 0
	s_mov_b32 s100, 0
	s_nop 0
	v_writelane_b32 v255, s100, 43
	v_writelane_b32 v255, s100, 46
	v_readlane_b32 s14, v255, 14
	s_cmp_lg_u32 s14, 3
	s_cselect_b64 s[10:11], -1, 0
	v_readlane_b32 s15, v255, 15
	v_writelane_b32 v255, s10, 18
	v_cvt_f32_u32_e32 v1, s14
	v_mul_f32_e32 v1, 0xbe99999a, v1
	v_writelane_b32 v255, s11, 19
	s_lshl_b32 s10, s14, 6
	s_mov_b32 s6, s10
	s_mov_b32 s11, s31
	v_writelane_b32 v255, s6, 20
	s_lshl_b64 s[10:11], s[10:11], 2
	v_mul_f32_e32 v2, 0x3fb8aa3b, v1
	v_writelane_b32 v255, s7, 21
	v_readlane_b32 s6, v254, 21
	s_add_u32 s10, s6, s10
	v_readlane_b32 s6, v254, 22
	s_addc_u32 s11, s6, s11
	v_writelane_b32 v255, s10, 22
	s_cmp_eq_u32 s14, 3
	s_cselect_b32 s6, 0, 16
	v_writelane_b32 v255, s11, 23
	s_mov_b64 s[10:11], s[0:1]
	s_cselect_b32 s10, 0, 64
	s_or_b32 s11, s6, 64
	v_writelane_b32 v255, s11, 24
	s_add_i32 s11, s11, s10
	v_writelane_b32 v255, s11, 25
	s_addk_i32 s11, 0x280
	v_writelane_b32 v255, s11, 26
	s_add_i32 s11, s11, s6
	v_writelane_b32 v255, s11, 27
	s_add_i32 s11, s11, s6
	v_writelane_b32 v255, s11, 28
	s_add_i32 s11, s11, s6
	s_add_i32 s18, s11, 0x180
	v_writelane_b32 v255, s18, 29
	s_add_i32 s18, s11, 0x280
	v_writelane_b32 v255, s18, 30
	v_writelane_b32 v255, s11, 31
	s_add_i32 s34, s11, 0x380
	s_mov_b32 s11, 0x3fb8aa3b
	v_fma_f32 v3, v1, s11, -v2
	v_rndne_f32_e32 v4, v2
	v_fmac_f32_e32 v3, 0x32a5705f, v1
	v_sub_f32_e32 v2, v2, v4
	v_add_f32_e32 v2, v2, v3
	v_exp_f32_e32 v2, v2
	v_cvt_i32_f32_e32 v3, v4
	s_lshl_b64 s[26:27], s[14:15], 12
	v_writelane_b32 v255, s26, 32
	s_mov_b32 s11, 0xc2ce8ed0
	v_ldexp_f32 v2, v2, v3
	v_writelane_b32 v255, s27, 33
	s_mul_i32 s26, s14, 0x3c00
	s_mov_b32 s27, s31
	v_writelane_b32 v255, s26, 34
	v_cmp_ngt_f32_e32 vcc, s11, v1
	s_mov_b32 s11, 0x42b17218
	v_writelane_b32 v255, s27, 35
	v_cndmask_b32_e32 v2, 0, v2, vcc
	v_cmp_nlt_f32_e32 vcc, s11, v1
	s_lshl_b32 s14, s14, 7
	s_mov_b32 s15, s31
	s_lshl_b32 s10, s10, 2
	s_lshl_b32 s6, s6, 4
	v_cndmask_b32_e32 v1, v220, v2, vcc
	v_mov_b32_e32 v2, 0x3f4ccccd
	v_writelane_b32 v255, s14, 36
	s_add_i32 s10, s10, s6
	v_fmamk_f32 v236, v1, 0xbf19999a, v2
	v_writelane_b32 v255, s15, 37
	s_xor_b32 s6, s10, 0xffffeb01
	v_sub_f32_e32 v227, 1.0, v236
	v_writelane_b32 v255, s6, 38
	s_branch .LBB0_484

.LBB0_747:
	s_and_b64 vcc, exec, s[10:11]
	s_cbranch_vccz .LBB0_751
	v_mov_b32_e32 v10, v232
	v_and_b32_e32 v181, 63, v10
	s_load_dwordx2 s[42:43], s[44:45], 0xb0
	s_waitcnt lgkmcnt(0)
	s_add_i32 s6, s37, s48
	s_lshl_b32 s14, s36, 7
	s_lshl_b32 s30, s36, 8
	v_readlane_b32 s11, v255, 21
	s_add_u32 s10, s42, s47
	s_addc_u32 s11, s43, s46
	s_add_u32 s36, s10, s30
	s_addc_u32 s37, s11, 0
	s_lshl_b32 s10, s27, 10
	s_or_b32 s10, s14, s10
	s_mul_hi_i32 s11, s10, 0x2200
	s_mulk_i32 s10, 0x2200
	v_ashrrev_i32_e32 v50, 4, v10
	s_add_u32 s10, s42, s10
	v_ashrrev_i32_e32 v51, 31, v50
	v_and_b32_e32 v177, 15, v10
	s_addc_u32 s11, s43, s11
	v_lshlrev_b64 v[52:53], 11, v[50:51]
	s_add_u32 s40, s10, 0xe010000
	v_lshl_add_u64 v[2:3], s[36:37], 0, v[52:53]
	v_lshlrev_b32_e32 v124, 4, v177
	v_mov_b32_e32 v125, v0
	s_addc_u32 s41, s11, 0
	v_lshl_add_u64 v[2:3], v[2:3], 0, v[124:125]
	s_mov_b32 s15, 0x16810000
	v_mov_b64_e32 v[4:5], s[40:41]
	s_movk_i32 s35, 0x2200
	v_add_co_u32_e32 v6, vcc, s15, v2
	v_mad_i64_i32 v[4:5], s[36:37], v50, s35, v[4:5]
	s_nop 0
	v_addc_co_u32_e32 v7, vcc, 0, v3, vcc
	s_mov_b32 s15, 0x16820000
	v_lshl_add_u64 v[4:5], v[4:5], 0, v[124:125]
	global_load_dwordx4 v[18:21], v[6:7], off
	global_load_dwordx4 v[22:25], v[4:5], off
	v_add_co_u32_e32 v6, vcc, s15, v2
	s_mov_b32 s15, 0x44000
	s_nop 0
	v_addc_co_u32_e32 v7, vcc, 0, v3, vcc
	v_add_co_u32_e32 v8, vcc, s15, v4
	s_mov_b32 s15, 0x16830000
	s_nop 0
	v_addc_co_u32_e32 v9, vcc, 0, v5, vcc
	global_load_dwordx4 v[26:29], v[6:7], off
	global_load_dwordx4 v[30:33], v[8:9], off
	v_add_co_u32_e32 v6, vcc, s15, v2
	s_mov_b32 s15, 0x88000
	s_nop 0
	v_addc_co_u32_e32 v7, vcc, 0, v3, vcc
	v_add_co_u32_e32 v8, vcc, s15, v4
	s_mov_b32 s15, 0x16840000
	s_nop 0
	v_addc_co_u32_e32 v9, vcc, 0, v5, vcc
	v_add_co_u32_e32 v2, vcc, s15, v2
	s_mov_b32 s15, 0xcc000
	s_nop 0
	v_addc_co_u32_e32 v3, vcc, 0, v3, vcc
	v_add_co_u32_e32 v4, vcc, s15, v4
	global_load_dwordx4 v[34:37], v[6:7], off
	global_load_dwordx4 v[38:41], v[8:9], off
	v_addc_co_u32_e32 v5, vcc, 0, v5, vcc
	global_load_dwordx4 v[42:45], v[2:3], off
	global_load_dwordx4 v[46:49], v[4:5], off
	v_ashrrev_i32_e32 v4, 2, v10
	v_and_b32_e32 v4, 0xffffffe0, v4
	v_add_u32_e32 v180, s6, v4
	v_ashrrev_i32_e32 v182, 6, v10
	v_and_b32_e32 v179, 1, v182
	v_mov_b32_e32 v55, v0
	v_lshlrev_b32_e32 v54, 7, v179
	v_and_b32_e32 v56, 48, v10
	v_mov_b32_e32 v57, v0
	s_mov_b32 s6, 0x14610000
	s_mov_b64 s[36:37], 0x14610000
	v_and_b32_e32 v2, 31, v223
	v_or_b32_e32 v2, v180, v2
	v_bfe_u32 v178, v10, 4, 2
	v_lshlrev_b32_e32 v51, 1, v50
	v_ashrrev_i32_e32 v3, 31, v2
	v_lshlrev_b64 v[2:3], 11, v[2:3]
	v_lshl_add_u64 v[2:3], s[42:43], 0, v[2:3]
	v_lshl_add_u64 v[2:3], v[2:3], 0, s[30:31]
	v_lshl_add_u64 v[2:3], v[2:3], 0, v[54:55]
	v_lshrrev_b32_e32 v55, 1, v50
	v_and_b32_e32 v56, 32, v232
	v_lshrrev_b32_e32 v56, 1, v56
	v_lshl_add_u64 v[6:7], v[2:3], 0, v[56:57]
	v_add_co_u32_e32 v4, vcc, s6, v6
	s_mov_b32 s6, 0x14610020
	s_nop 0
	v_addc_co_u32_e32 v5, vcc, 0, v7, vcc
	v_lshl_add_u64 v[2:3], v[6:7], 0, s[36:37]
	v_add_co_u32_e32 v6, vcc, s6, v6
	global_load_dwordx4 v[10:13], v[4:5], off
	s_nop 0
	global_load_dwordx4 v[2:5], v[2:3], off offset:64
	v_addc_co_u32_e32 v7, vcc, 0, v7, vcc
	global_load_dwordx4 v[14:17], v[6:7], off
	s_nop 0
	global_load_dwordx4 v[6:9], v[6:7], off offset:64
	v_and_b32_e32 v51, 8, v51
	v_and_b32_e32 v55, 4, v55
	v_and_b32_e32 v57, 0xffffff3, v50
	v_or3_b32 v51, v57, v51, v55
	s_movk_i32 s6, 0x110
	v_mul_lo_u32 v55, v50, s6
	v_mad_u64_u32 v[126:127], s[36:37], v51, s6, v[124:125]
	s_mov_b32 s6, 0x11000
	v_add3_u32 v127, v55, v124, s6
	v_add_u32_e32 v51, 0, v126
	v_add_u32_e32 v55, 0, v127
	s_waitcnt vmcnt(11)
	ds_write_b128 v51, v[18:21]
	s_waitcnt vmcnt(10)
	ds_write_b128 v55, v[22:25]
	s_waitcnt vmcnt(9)
	ds_write_b128 v51, v[26:29] offset:8704
	s_waitcnt vmcnt(8)
	ds_write_b128 v55, v[30:33] offset:8704
	s_waitcnt vmcnt(7)
	ds_write_b128 v51, v[34:37] offset:17408
	s_waitcnt vmcnt(6)
	ds_write_b128 v55, v[38:41] offset:17408
	s_waitcnt vmcnt(5)
	ds_write_b128 v51, v[42:45] offset:26112
	s_waitcnt vmcnt(4)
	ds_write_b128 v55, v[46:49] offset:26112
	s_add_i32 s6, 0, 0x11000
	v_mul_u32_u24_e32 v19, 0x110, v177
	v_add3_u32 v183, s6, v56, v19
	s_lshl_b32 s6, s26, 3
	s_and_b32 s6, s6, 0x700
	s_add_u32 s6, s42, s6
	v_add_u32_e32 v18, 0, v54
	s_addc_u32 s18, s43, 0
	v_add3_u32 v137, v18, v56, v19
	s_add_u32 s26, s6, s47
	v_mov_b64_e32 v[18:19], s[10:11]
	s_addc_u32 s27, s18, s46
	v_mad_i64_i32 v[130:131], s[10:11], v50, s35, v[18:19]
	v_mov_b32_e32 v18, 0
	s_mov_b32 s15, 0
	v_lshl_add_u64 v[128:129], s[26:27], 0, v[52:53]
	v_mov_b32_e32 v19, v18
	v_mov_b32_e32 v20, v18
	v_mov_b32_e32 v21, v18
	v_mov_b32_e32 v22, v18
	v_mov_b32_e32 v23, v18
	v_mov_b32_e32 v24, v18
	v_mov_b32_e32 v25, v18
	v_mov_b32_e32 v26, v18
	v_mov_b32_e32 v27, v18
	v_mov_b32_e32 v28, v18
	v_mov_b32_e32 v29, v18
	v_mov_b32_e32 v30, v18
	v_mov_b32_e32 v31, v18
	v_mov_b32_e32 v32, v18
	v_mov_b32_e32 v33, v18
	v_mov_b32_e32 v38, v18
	v_mov_b32_e32 v39, v18
	v_mov_b32_e32 v40, v18
	v_mov_b32_e32 v41, v18
	v_mov_b32_e32 v46, v18
	v_mov_b32_e32 v47, v18
	v_mov_b32_e32 v48, v18
	v_mov_b32_e32 v49, v18
	v_mov_b32_e32 v62, v18
	v_mov_b32_e32 v63, v18
	v_mov_b32_e32 v64, v18
	v_mov_b32_e32 v65, v18
	v_mov_b32_e32 v74, v18
	v_mov_b32_e32 v75, v18
	v_mov_b32_e32 v76, v18
	v_mov_b32_e32 v77, v18
	v_mov_b32_e32 v34, v18
	v_mov_b32_e32 v35, v18
	v_mov_b32_e32 v36, v18
	v_mov_b32_e32 v37, v18
	v_mov_b32_e32 v42, v18
	v_mov_b32_e32 v43, v18
	v_mov_b32_e32 v44, v18
	v_mov_b32_e32 v45, v18
	v_mov_b32_e32 v50, v18
	v_mov_b32_e32 v51, v18
	v_mov_b32_e32 v52, v18
	v_mov_b32_e32 v53, v18
	v_mov_b32_e32 v54, v18
	v_mov_b32_e32 v55, v18
	v_mov_b32_e32 v56, v18
	v_mov_b32_e32 v57, v18
	v_mov_b32_e32 v58, v18
	v_mov_b32_e32 v59, v18
	v_mov_b32_e32 v60, v18
	v_mov_b32_e32 v61, v18
	v_mov_b32_e32 v66, v18
	v_mov_b32_e32 v67, v18
	v_mov_b32_e32 v68, v18
	v_mov_b32_e32 v69, v18
	v_mov_b32_e32 v70, v18
	v_mov_b32_e32 v71, v18
	v_mov_b32_e32 v72, v18
	v_mov_b32_e32 v73, v18
	v_mov_b32_e32 v78, v18
	v_mov_b32_e32 v79, v18
	v_mov_b32_e32 v80, v18
	v_mov_b32_e32 v81, v18
	v_mov_b32_e32 v122, v18
	v_mov_b32_e32 v123, v18
	s_mov_b32 s11, 0xe054000
	s_mov_b32 s18, 0x16870000
	s_mov_b32 s26, 0xe098000
	s_mov_b32 s27, 0x16880000
	s_mov_b32 s30, 0xe0dc000
	s_mov_b64 s[36:37], 0x40000
	s_waitcnt lgkmcnt(0)
	s_barrier
	s_waitcnt vmcnt(0) lgkmcnt(0)
	v_writelane_b32 v175, s64, 0
	v_writelane_b32 v175, s65, 1
	v_writelane_b32 v175, s66, 2
	v_writelane_b32 v175, s67, 3
	v_writelane_b32 v175, s68, 4
	v_writelane_b32 v175, s69, 5
	v_writelane_b32 v175, s70, 6
	v_writelane_b32 v175, s71, 7
	v_writelane_b32 v175, s72, 8
	v_writelane_b32 v175, s73, 9
	v_writelane_b32 v175, s74, 10
	v_writelane_b32 v175, s75, 11
	v_writelane_b32 v175, s76, 12
	v_writelane_b32 v175, s77, 13
	v_writelane_b32 v175, s78, 14
	v_writelane_b32 v175, s79, 15
	v_lshl_add_u64 v[138:139], v[128:129], 0, v[124:125]
	v_lshl_add_u64 v[140:141], v[130:131], 0, v[124:125]
	s_nop 1
	v_readfirstlane_b32 s64, v138
	v_readfirstlane_b32 s65, v139
	v_readfirstlane_b32 s72, v140
	v_readfirstlane_b32 s73, v141
	s_nop 3
	v_subrev_u32_e32 v124, s64, v138
	v_subrev_u32_e32 v125, s72, v140
	s_add_u32 s66, s64, s97
	s_addc_u32 s67, s65, 0
	s_add_u32 s68, s64, s18
	s_addc_u32 s69, s65, 0
	s_add_u32 s70, s64, s27
	s_addc_u32 s71, s65, 0
	s_add_u32 s64, s64, s96
	s_addc_u32 s65, s65, 0
	s_add_u32 s74, s72, s11
	s_addc_u32 s75, s73, 0
	s_add_u32 s74, s74, 0x100
	s_addc_u32 s75, s75, 0
	s_add_u32 s76, s72, s26
	s_addc_u32 s77, s73, 0
	s_add_u32 s76, s76, 0x100
	s_addc_u32 s77, s77, 0
	s_add_u32 s78, s72, s30
	s_addc_u32 s79, s73, 0
	s_add_u32 s78, s78, 0x100
	s_addc_u32 s79, s79, 0
	s_add_u32 s72, s72, s91
	s_addc_u32 s73, s73, 0
	s_add_u32 s72, s72, 0x100
	s_addc_u32 s73, s73, 0
	v_and_b32_e32 v137, 31, v223
	v_mul_u32_u24_e32 v137, 0x110, v137
	v_lshrrev_b32_e32 v183, 5, v223
	v_lshl_add_u32 v137, v183, 4, v137
	v_add_u32_e32 v183, 0x11000, v137
	v_lshl_add_u32 v137, v179, 7, v137
	s_mov_b32 s15, 0
	s_nop 4
	.p2align 6
.Lattn_nf_loop:
	s_and_b32 s10, s15, 1
	s_mul_i32 s6, s10, 0x8800
	v_add_u32_e32 v136, s6, v137
	v_add_u32_e32 v170, s6, v183
	s_sub_u32 s10, 0x8800, s6
	ds_read_b128 v[98:101], v136 offset:0
	ds_read_b128 v[102:105], v136 offset:32
	ds_read_b128 v[106:109], v136 offset:64
	ds_read_b128 v[110:113], v136 offset:96
	v_add_u32_e32 v171, s10, v126
	v_add_u32_e32 v173, s10, v127
	global_load_dwordx4 v[82:85], v124, s[64:65]
	global_load_dwordx4 v[86:89], v124, s[66:67]
	global_load_dwordx4 v[90:93], v124, s[68:69]
	global_load_dwordx4 v[94:97], v124, s[70:71]
	v_add_u32_e32 v124, s36, v124
	s_waitcnt lgkmcnt(3)
	v_mfma_f32_32x32x16_bf16 v[138:153], v[98:101], v[10:13], 0
	ds_read_b128 v[98:101], v136 offset:8704
	s_waitcnt lgkmcnt(3)
	v_mfma_f32_32x32x16_bf16 v[138:153], v[102:105], v[14:17], v[138:153]
	ds_read_b128 v[102:105], v136 offset:8736
	s_waitcnt lgkmcnt(3)
	v_mfma_f32_32x32x16_bf16 v[138:153], v[106:109], v[2:5], v[138:153]
	ds_read_b128 v[106:109], v136 offset:8768
	s_waitcnt lgkmcnt(3)
	v_mfma_f32_32x32x16_bf16 v[138:153], v[110:113], v[6:9], v[138:153]
	ds_read_b128 v[110:113], v136 offset:8800
	ds_read_b128 v[128:131], v170 offset:0
	ds_read_b128 v[184:187], v170 offset:8704
	ds_read_b128 v[188:191], v170 offset:17408
	ds_read_b128 v[192:195], v170 offset:26112
	s_waitcnt lgkmcnt(7)
	v_mfma_f32_32x32x16_bf16 v[154:169], v[98:101], v[10:13], 0
	ds_read_b128 v[98:101], v136 offset:17408
	s_nop 3
	v_exp_f32_e32 v138, v138
	v_exp_f32_e32 v139, v139
	v_exp_f32_e32 v140, v140
	v_exp_f32_e32 v141, v141
	v_exp_f32_e32 v142, v142
	v_exp_f32_e32 v143, v143
	s_waitcnt lgkmcnt(7)
	v_mfma_f32_32x32x16_bf16 v[154:169], v[102:105], v[14:17], v[154:169]
	ds_read_b128 v[102:105], v136 offset:17440
	v_exp_f32_e32 v144, v144
	v_exp_f32_e32 v145, v145
	v_add_f32_e32 v122, v138, v122
	v_add_f32_e32 v122, v139, v122
	v_add_f32_e32 v122, v140, v122
	v_add_f32_e32 v122, v141, v122
	v_add_f32_e32 v122, v142, v122
	v_add_f32_e32 v122, v143, v122
	v_add_f32_e32 v122, v144, v122
	v_add_f32_e32 v122, v145, v122
	v_cvt_pk_bf16_f32 v114, v138, v139
	v_cvt_pk_bf16_f32 v115, v140, v141
	v_cvt_pk_bf16_f32 v116, v142, v143
	v_cvt_pk_bf16_f32 v117, v144, v145
	ds_read_b128 v[196:199], v170 offset:32
	ds_read_b128 v[216:219], v170 offset:8736
	ds_read_b128 v[200:203], v170 offset:17440
	ds_read_b128 v[204:207], v170 offset:26144
	s_waitcnt lgkmcnt(11)
	v_mfma_f32_32x32x16_bf16 v[154:169], v[106:109], v[2:5], v[154:169]
	ds_read_b128 v[106:109], v136 offset:17472
	v_exp_f32_e32 v146, v146
	v_exp_f32_e32 v147, v147
	s_waitcnt lgkmcnt(11)
	v_mfma_f32_32x32x16_bf16 v[154:169], v[110:113], v[6:9], v[154:169]
	ds_read_b128 v[110:113], v136 offset:17504
	v_exp_f32_e32 v148, v148
	v_exp_f32_e32 v149, v149
	s_waitcnt lgkmcnt(11)
	v_mfma_f32_32x32x16_bf16 v[18:33], v[128:131], v[114:117], v[18:33]
	v_exp_f32_e32 v150, v150
	v_exp_f32_e32 v151, v151
	s_waitcnt lgkmcnt(10)
	v_mfma_f32_32x32x16_bf16 v[34:49], v[184:187], v[114:117], v[34:49]
	v_exp_f32_e32 v152, v152
	v_exp_f32_e32 v153, v153
	s_waitcnt lgkmcnt(9)
	v_mfma_f32_32x32x16_bf16 v[50:65], v[188:191], v[114:117], v[50:65]
	v_add_f32_e32 v122, v146, v122
	v_add_f32_e32 v122, v147, v122
	v_add_f32_e32 v122, v148, v122
	v_add_f32_e32 v122, v149, v122
	s_waitcnt lgkmcnt(8)
	v_mfma_f32_32x32x16_bf16 v[66:81], v[192:195], v[114:117], v[66:81]
	v_add_f32_e32 v122, v150, v122
	v_add_f32_e32 v122, v151, v122
	v_add_f32_e32 v122, v152, v122
	v_add_f32_e32 v122, v153, v122
	v_cvt_pk_bf16_f32 v118, v146, v147
	v_cvt_pk_bf16_f32 v119, v148, v149
	v_cvt_pk_bf16_f32 v120, v150, v151
	v_cvt_pk_bf16_f32 v121, v152, v153
	ds_read_b128 v[128:131], v170 offset:64
	ds_read_b128 v[184:187], v170 offset:8768
	ds_read_b128 v[188:191], v170 offset:17472
	ds_read_b128 v[192:195], v170 offset:26176
	s_waitcnt lgkmcnt(11)
	v_mfma_f32_32x32x16_bf16 v[138:153], v[98:101], v[10:13], 0
	ds_read_b128 v[98:101], v136 offset:26112
	v_exp_f32_e32 v154, v154
	v_exp_f32_e32 v155, v155
	s_waitcnt lgkmcnt(11)
	v_mfma_f32_32x32x16_bf16 v[138:153], v[102:105], v[14:17], v[138:153]
	ds_read_b128 v[102:105], v136 offset:26144
	v_exp_f32_e32 v156, v156
	v_exp_f32_e32 v157, v157
	s_waitcnt lgkmcnt(11)
	v_mfma_f32_32x32x16_bf16 v[18:33], v[196:199], v[118:121], v[18:33]
	v_exp_f32_e32 v158, v158
	v_exp_f32_e32 v159, v159
	s_waitcnt lgkmcnt(10)
	v_mfma_f32_32x32x16_bf16 v[34:49], v[216:219], v[118:121], v[34:49]
	v_exp_f32_e32 v160, v160
	v_exp_f32_e32 v161, v161
	s_waitcnt lgkmcnt(9)
	v_mfma_f32_32x32x16_bf16 v[50:65], v[200:203], v[118:121], v[50:65]
	v_add_f32_e32 v122, v154, v122
	v_add_f32_e32 v122, v155, v122
	v_add_f32_e32 v122, v156, v122
	v_add_f32_e32 v122, v157, v122
	s_waitcnt lgkmcnt(8)
	v_mfma_f32_32x32x16_bf16 v[66:81], v[204:207], v[118:121], v[66:81]
	v_add_f32_e32 v122, v158, v122
	v_add_f32_e32 v122, v159, v122
	v_add_f32_e32 v122, v160, v122
	v_add_f32_e32 v122, v161, v122
	v_cvt_pk_bf16_f32 v114, v154, v155
	v_cvt_pk_bf16_f32 v115, v156, v157
	v_cvt_pk_bf16_f32 v116, v158, v159
	v_cvt_pk_bf16_f32 v117, v160, v161
	ds_read_b128 v[196:199], v170 offset:96
	ds_read_b128 v[216:219], v170 offset:8800
	ds_read_b128 v[200:203], v170 offset:17504
	ds_read_b128 v[204:207], v170 offset:26208
	s_waitcnt lgkmcnt(11)
	v_mfma_f32_32x32x16_bf16 v[138:153], v[106:109], v[2:5], v[138:153]
	ds_read_b128 v[106:109], v136 offset:26176
	v_exp_f32_e32 v162, v162
	v_exp_f32_e32 v163, v163
	s_waitcnt lgkmcnt(11)
	v_mfma_f32_32x32x16_bf16 v[138:153], v[110:113], v[6:9], v[138:153]
	ds_read_b128 v[110:113], v136 offset:26208
	v_exp_f32_e32 v164, v164
	v_exp_f32_e32 v165, v165
	s_waitcnt lgkmcnt(11)
	v_mfma_f32_32x32x16_bf16 v[18:33], v[128:131], v[114:117], v[18:33]
	v_exp_f32_e32 v166, v166
	v_exp_f32_e32 v167, v167
	s_waitcnt lgkmcnt(10)
	v_mfma_f32_32x32x16_bf16 v[34:49], v[184:187], v[114:117], v[34:49]
	v_exp_f32_e32 v168, v168
	v_exp_f32_e32 v169, v169
	s_waitcnt lgkmcnt(9)
	v_mfma_f32_32x32x16_bf16 v[50:65], v[188:191], v[114:117], v[50:65]
	v_add_f32_e32 v122, v162, v122
	v_add_f32_e32 v122, v163, v122
	v_add_f32_e32 v122, v164, v122
	v_add_f32_e32 v122, v165, v122
	s_waitcnt lgkmcnt(8)
	v_mfma_f32_32x32x16_bf16 v[66:81], v[192:195], v[114:117], v[66:81]
	v_add_f32_e32 v122, v166, v122
	v_add_f32_e32 v122, v167, v122
	v_add_f32_e32 v122, v168, v122
	v_add_f32_e32 v122, v169, v122
	v_cvt_pk_bf16_f32 v118, v162, v163
	v_cvt_pk_bf16_f32 v119, v164, v165
	v_cvt_pk_bf16_f32 v120, v166, v167
	v_cvt_pk_bf16_f32 v121, v168, v169
	ds_read_b128 v[128:131], v170 offset:128
	ds_read_b128 v[184:187], v170 offset:8832
	ds_read_b128 v[188:191], v170 offset:17536
	ds_read_b128 v[192:195], v170 offset:26240
	s_waitcnt lgkmcnt(11)
	v_mfma_f32_32x32x16_bf16 v[154:169], v[98:101], v[10:13], 0
	v_exp_f32_e32 v138, v138
	s_waitcnt lgkmcnt(10)
	v_mfma_f32_32x32x16_bf16 v[154:169], v[102:105], v[14:17], v[154:169]
	v_exp_f32_e32 v139, v139
	v_exp_f32_e32 v140, v140
	s_waitcnt lgkmcnt(9)
	v_mfma_f32_32x32x16_bf16 v[18:33], v[196:199], v[118:121], v[18:33]
	v_exp_f32_e32 v141, v141
	v_exp_f32_e32 v142, v142
	s_waitcnt vmcnt(3)
	ds_write_b128 v171, v[82:85] offset:0
	s_waitcnt vmcnt(2)
	ds_write_b128 v171, v[86:89] offset:8704
	s_waitcnt vmcnt(1)
	ds_write_b128 v171, v[90:93] offset:17408
	s_waitcnt vmcnt(0)
	ds_write_b128 v171, v[94:97] offset:26112
	v_exp_f32_e32 v143, v143
	s_waitcnt lgkmcnt(12)
	v_mfma_f32_32x32x16_bf16 v[34:49], v[216:219], v[118:121], v[34:49]
	v_exp_f32_e32 v144, v144
	v_exp_f32_e32 v145, v145
	v_add_f32_e32 v122, v138, v122
	s_waitcnt lgkmcnt(11)
	v_mfma_f32_32x32x16_bf16 v[50:65], v[200:203], v[118:121], v[50:65]
	v_add_f32_e32 v122, v139, v122
	v_add_f32_e32 v122, v140, v122
	v_add_f32_e32 v122, v141, v122
	s_waitcnt lgkmcnt(10)
	v_mfma_f32_32x32x16_bf16 v[66:81], v[204:207], v[118:121], v[66:81]
	v_add_f32_e32 v122, v142, v122
	v_add_f32_e32 v122, v143, v122
	v_add_f32_e32 v122, v144, v122
	v_add_f32_e32 v122, v145, v122
	v_cvt_pk_bf16_f32 v114, v138, v139
	v_cvt_pk_bf16_f32 v115, v140, v141
	v_cvt_pk_bf16_f32 v116, v142, v143
	v_cvt_pk_bf16_f32 v117, v144, v145
	ds_read_b128 v[196:199], v170 offset:160
	ds_read_b128 v[216:219], v170 offset:8864
	ds_read_b128 v[200:203], v170 offset:17568
	ds_read_b128 v[204:207], v170 offset:26272
	s_waitcnt lgkmcnt(13)
	v_mfma_f32_32x32x16_bf16 v[154:169], v[106:109], v[2:5], v[154:169]
	v_exp_f32_e32 v146, v146
	s_waitcnt lgkmcnt(12)
	v_mfma_f32_32x32x16_bf16 v[154:169], v[110:113], v[6:9], v[154:169]
	v_exp_f32_e32 v147, v147
	v_exp_f32_e32 v148, v148
	s_waitcnt lgkmcnt(11)
	v_mfma_f32_32x32x16_bf16 v[18:33], v[128:131], v[114:117], v[18:33]
	v_exp_f32_e32 v149, v149
	v_exp_f32_e32 v150, v150
	global_load_dwordx4 v[82:85], v125, s[72:73]
	global_load_dwordx4 v[86:89], v125, s[74:75]
	global_load_dwordx4 v[90:93], v125, s[76:77]
	global_load_dwordx4 v[94:97], v125, s[78:79]
	v_add_u32_e32 v125, s38, v125
	v_exp_f32_e32 v151, v151
	s_waitcnt lgkmcnt(10)
	v_mfma_f32_32x32x16_bf16 v[34:49], v[184:187], v[114:117], v[34:49]
	v_exp_f32_e32 v152, v152
	v_exp_f32_e32 v153, v153
	v_add_f32_e32 v122, v146, v122
	s_waitcnt lgkmcnt(9)
	v_mfma_f32_32x32x16_bf16 v[50:65], v[188:191], v[114:117], v[50:65]
	v_add_f32_e32 v122, v147, v122
	v_add_f32_e32 v122, v148, v122
	v_add_f32_e32 v122, v149, v122
	s_waitcnt lgkmcnt(8)
	v_mfma_f32_32x32x16_bf16 v[66:81], v[192:195], v[114:117], v[66:81]
	v_add_f32_e32 v122, v150, v122
	v_add_f32_e32 v122, v151, v122
	v_add_f32_e32 v122, v152, v122
	v_add_f32_e32 v122, v153, v122
	v_cvt_pk_bf16_f32 v118, v146, v147
	v_cvt_pk_bf16_f32 v119, v148, v149
	v_cvt_pk_bf16_f32 v120, v150, v151
	v_cvt_pk_bf16_f32 v121, v152, v153
	ds_read_b128 v[128:131], v170 offset:192
	ds_read_b128 v[184:187], v170 offset:8896
	ds_read_b128 v[188:191], v170 offset:17600
	ds_read_b128 v[192:195], v170 offset:26304
	s_waitcnt lgkmcnt(7)
	v_mfma_f32_32x32x16_bf16 v[18:33], v[196:199], v[118:121], v[18:33]
	v_exp_f32_e32 v154, v154
	v_exp_f32_e32 v155, v155
	v_exp_f32_e32 v156, v156
	s_waitcnt lgkmcnt(6)
	v_mfma_f32_32x32x16_bf16 v[34:49], v[216:219], v[118:121], v[34:49]
	v_exp_f32_e32 v157, v157
	v_exp_f32_e32 v158, v158
	v_exp_f32_e32 v159, v159
	s_waitcnt lgkmcnt(5)
	v_mfma_f32_32x32x16_bf16 v[50:65], v[200:203], v[118:121], v[50:65]
	v_exp_f32_e32 v160, v160
	v_exp_f32_e32 v161, v161
	v_add_f32_e32 v122, v154, v122
	v_add_f32_e32 v122, v155, v122
	s_waitcnt lgkmcnt(4)
	v_mfma_f32_32x32x16_bf16 v[66:81], v[204:207], v[118:121], v[66:81]
	v_add_f32_e32 v122, v156, v122
	v_add_f32_e32 v122, v157, v122
	v_add_f32_e32 v122, v158, v122
	v_add_f32_e32 v122, v159, v122
	v_add_f32_e32 v122, v160, v122
	v_add_f32_e32 v122, v161, v122
	v_cvt_pk_bf16_f32 v114, v154, v155
	v_cvt_pk_bf16_f32 v115, v156, v157
	v_cvt_pk_bf16_f32 v116, v158, v159
	v_cvt_pk_bf16_f32 v117, v160, v161
	ds_read_b128 v[196:199], v170 offset:224
	ds_read_b128 v[216:219], v170 offset:8928
	ds_read_b128 v[200:203], v170 offset:17632
	ds_read_b128 v[204:207], v170 offset:26336
	s_waitcnt lgkmcnt(7)
	v_mfma_f32_32x32x16_bf16 v[18:33], v[128:131], v[114:117], v[18:33]
	v_exp_f32_e32 v162, v162
	v_exp_f32_e32 v163, v163
	v_exp_f32_e32 v164, v164
	s_waitcnt lgkmcnt(6)
	v_mfma_f32_32x32x16_bf16 v[34:49], v[184:187], v[114:117], v[34:49]
	v_exp_f32_e32 v165, v165
	v_exp_f32_e32 v166, v166
	v_exp_f32_e32 v167, v167
	s_waitcnt lgkmcnt(5)
	v_mfma_f32_32x32x16_bf16 v[50:65], v[188:191], v[114:117], v[50:65]
	v_exp_f32_e32 v168, v168
	v_exp_f32_e32 v169, v169
	v_add_f32_e32 v122, v162, v122
	v_add_f32_e32 v122, v163, v122
	s_waitcnt lgkmcnt(4)
	v_mfma_f32_32x32x16_bf16 v[66:81], v[192:195], v[114:117], v[66:81]
	v_add_f32_e32 v122, v164, v122
	v_add_f32_e32 v122, v165, v122
	v_add_f32_e32 v122, v166, v122
	v_add_f32_e32 v122, v167, v122
	v_add_f32_e32 v122, v168, v122
	v_add_f32_e32 v122, v169, v122
	v_cvt_pk_bf16_f32 v118, v162, v163
	v_cvt_pk_bf16_f32 v119, v164, v165
	v_cvt_pk_bf16_f32 v120, v166, v167
	v_cvt_pk_bf16_f32 v121, v168, v169
	s_waitcnt lgkmcnt(3)
	s_nop 0
	v_mfma_f32_32x32x16_bf16 v[18:33], v[196:199], v[118:121], v[18:33]
	s_waitcnt lgkmcnt(2)
	v_mfma_f32_32x32x16_bf16 v[34:49], v[216:219], v[118:121], v[34:49]
	s_waitcnt vmcnt(3)
	ds_write_b128 v173, v[82:85] offset:0
	s_waitcnt vmcnt(2)
	ds_write_b128 v173, v[86:89] offset:8704
	s_waitcnt vmcnt(1)
	ds_write_b128 v173, v[90:93] offset:17408
	s_waitcnt vmcnt(0)
	ds_write_b128 v173, v[94:97] offset:26112
	s_waitcnt lgkmcnt(5)
	v_mfma_f32_32x32x16_bf16 v[50:65], v[200:203], v[118:121], v[50:65]
	s_waitcnt lgkmcnt(4)
	v_mfma_f32_32x32x16_bf16 v[66:81], v[204:207], v[118:121], v[66:81]
	s_waitcnt lgkmcnt(0)
	s_barrier
	s_add_i32 s15, s15, 1
	s_cmp_eq_u32 s15, 34
	s_cbranch_scc0 .Lattn_nf_loop
	v_readlane_b32 s64, v175, 0
	v_readlane_b32 s65, v175, 1
	v_readlane_b32 s66, v175, 2
	v_readlane_b32 s67, v175, 3
	v_readlane_b32 s68, v175, 4
	v_readlane_b32 s69, v175, 5
	v_readlane_b32 s70, v175, 6
	v_readlane_b32 s71, v175, 7
	v_readlane_b32 s72, v175, 8
	v_readlane_b32 s73, v175, 9
	v_readlane_b32 s74, v175, 10
	v_readlane_b32 s75, v175, 11
	v_readlane_b32 s76, v175, 12
	v_readlane_b32 s77, v175, 13
	v_readlane_b32 s78, v175, 14
	v_readlane_b32 s79, v175, 15
	s_nop 4
	s_mov_b32 s10, 0x3fb8aa3b
	s_mov_b32 s11, 0xc2ce8ed0
	s_mov_b32 s6, 0x42b17218
	v_cmp_eq_u32_e64 s[40:41], 0, v179
	s_lshl_b32 s30, s14, 1
	v_lshlrev_b32_e32 v196, 3, v178
	v_mov_b32_e32 v197, 0
	v_lshlrev_b32_e32 v198, 4, v179
	v_or3_b32 v198, v198, v177, v180
	v_ashrrev_i32_e32 v199, 31, v198
	v_lshlrev_b64 v[198:199], 11, v[198:199]
	s_mov_b64 s[100:101], 0x18a10000
	v_lshl_add_u64 v[198:199], s[42:43], 0, v[198:199]
	v_lshl_add_u64 v[198:199], v[198:199], 0, s[30:31]
	v_lshl_add_u64 v[198:199], v[198:199], 0, v[196:197]
	v_lshl_add_u64 v[198:199], v[198:199], 0, s[100:101]
	global_load_dwordx2 v[146:147], v[198:199], off
	global_load_dwordx2 v[148:149], v[198:199], off offset:32
	global_load_dwordx2 v[150:151], v[198:199], off offset:64
	global_load_dwordx2 v[152:153], v[198:199], off offset:96
	global_load_dwordx2 v[188:189], v[198:199], off offset:128
	global_load_dwordx2 v[190:191], v[198:199], off offset:160
	global_load_dwordx2 v[192:193], v[198:199], off offset:192
	global_load_dwordx2 v[194:195], v[198:199], off offset:224
	s_mov_b64 s[100:101], exec
	s_and_b64 exec, exec, s[4:5]
	s_cbranch_execz .Lpop_skip
	v_readlane_b32 s14, v255, 22
	v_readlane_b32 s15, v255, 23
	v_mov_b32_e32 v224, 1
	s_nop 4
	global_atomic_add v224, v0, v224, s[14:15] sc0
.Lpop_skip:
	s_mov_b64 exec, s[100:101]
	v_mov_b32_e32 v235, 1
	s_load_dwordx2 s[100:101], s[44:45], 0x80
	v_readlane_b32 s14, v255, 36
	v_readlane_b32 s15, v255, 37
	s_nop 3
	s_lshl_b64 s[14:15], s[14:15], 2
	s_waitcnt lgkmcnt(0)
	v_readlane_b32 s6, v255, 46
	v_readlane_b32 s10, v255, 45
	s_nop 3
	s_cmp_eq_u32 s6, 0
	s_cbranch_scc0 .Lattn_lam_have
	v_readlane_b32 s6, v255, 20
	s_nop 3
	v_or_b32_e32 v90, s6, v181
	v_lshlrev_b32_e32 v90, 2, v90
	s_load_dwordx2 s[10:11], s[44:45], 0x60
	s_waitcnt lgkmcnt(0)
	global_load_dword v91, v90, s[10:11]
	s_load_dwordx2 s[10:11], s[44:45], 0x68
	s_waitcnt lgkmcnt(0)
	global_load_dword v92, v90, s[10:11]
	s_load_dwordx2 s[10:11], s[44:45], 0x70
	s_waitcnt lgkmcnt(0)
	global_load_dword v93, v90, s[10:11]
	s_load_dwordx2 s[10:11], s[44:45], 0x78
	s_waitcnt lgkmcnt(0)
	global_load_dword v94, v90, s[10:11]
	s_waitcnt vmcnt(0)
	v_mul_f32_e32 v91, v91, v92
	v_mul_f32_e32 v93, v93, v94
	v_xor_b32_e32 v90, 1, v223
	v_lshlrev_b32_e32 v90, 2, v90
	ds_bpermute_b32 v92, v90, v91
	ds_bpermute_b32 v94, v90, v93
	s_waitcnt lgkmcnt(0)
	v_add_f32_e32 v91, v91, v92
	v_add_f32_e32 v93, v93, v94
	v_xor_b32_e32 v90, 2, v223
	v_lshlrev_b32_e32 v90, 2, v90
	ds_bpermute_b32 v92, v90, v91
	ds_bpermute_b32 v94, v90, v93
	s_waitcnt lgkmcnt(0)
	v_add_f32_e32 v91, v91, v92
	v_add_f32_e32 v93, v93, v94
	v_xor_b32_e32 v90, 4, v223
	v_lshlrev_b32_e32 v90, 2, v90
	ds_bpermute_b32 v92, v90, v91
	ds_bpermute_b32 v94, v90, v93
	s_waitcnt lgkmcnt(0)
	v_add_f32_e32 v91, v91, v92
	v_add_f32_e32 v93, v93, v94
	v_xor_b32_e32 v90, 8, v223
	v_lshlrev_b32_e32 v90, 2, v90
	ds_bpermute_b32 v92, v90, v91
	ds_bpermute_b32 v94, v90, v93
	s_waitcnt lgkmcnt(0)
	v_add_f32_e32 v91, v91, v92
	v_add_f32_e32 v93, v93, v94
	v_xor_b32_e32 v90, 16, v223
	v_lshlrev_b32_e32 v90, 2, v90
	ds_bpermute_b32 v92, v90, v91
	ds_bpermute_b32 v94, v90, v93
	s_waitcnt lgkmcnt(0)
	v_add_f32_e32 v91, v91, v92
	v_add_f32_e32 v93, v93, v94
	v_xor_b32_e32 v90, 32, v223
	v_lshlrev_b32_e32 v90, 2, v90
	ds_bpermute_b32 v92, v90, v91
	ds_bpermute_b32 v94, v90, v93
	s_waitcnt lgkmcnt(0)
	v_add_f32_e32 v91, v91, v92
	v_add_f32_e32 v93, v93, v94
	s_mov_b32 s10, 0x3fb8aa3b
	s_mov_b32 s11, 0xc2ce8ed0
	s_mov_b32 s6, 0x42b17218
	v_mul_f32_e32 v85, 0x3fb8aa3b, v91
	v_fma_f32 v86, v91, s10, -v85
	v_rndne_f32_e32 v87, v85
	v_fmac_f32_e32 v86, 0x32a5705f, v91
	v_sub_f32_e32 v85, v85, v87
	v_add_f32_e32 v85, v85, v86
	v_exp_f32_e32 v85, v85
	v_cvt_i32_f32_e32 v86, v87
	v_cmp_ngt_f32_e32 vcc, s11, v91
	s_nop 0
	v_ldexp_f32 v85, v85, v86
	s_nop 1
	v_cndmask_b32_e32 v85, 0, v85, vcc
	v_cmp_nlt_f32_e32 vcc, s6, v91
	s_nop 1
	v_cndmask_b32_e32 v88, v220, v85, vcc
	v_mul_f32_e32 v85, 0x3fb8aa3b, v93
	v_fma_f32 v86, v93, s10, -v85
	v_rndne_f32_e32 v87, v85
	v_fmac_f32_e32 v86, 0x32a5705f, v93
	v_sub_f32_e32 v85, v85, v87
	v_add_f32_e32 v85, v85, v86
	v_exp_f32_e32 v85, v85
	v_cvt_i32_f32_e32 v86, v87
	v_cmp_ngt_f32_e32 vcc, s11, v93
	s_nop 0
	v_ldexp_f32 v85, v85, v86
	s_nop 1
	v_cndmask_b32_e32 v85, 0, v85, vcc
	v_cmp_nlt_f32_e32 vcc, s6, v93
	s_nop 1
	v_cndmask_b32_e32 v89, v220, v85, vcc
	v_sub_f32_e32 v88, v88, v89
	v_add_f32_e32 v88, v236, v88
	s_nop 0
	v_readfirstlane_b32 s10, v88
	s_mov_b32 s6, 1
	s_nop 3
	v_writelane_b32 v255, s10, 45
	v_writelane_b32 v255, s6, 46
.Lattn_lam_have:
	s_nop 1
	v_mov_b32_e32 v88, s10
	s_nop 0
	v_cndmask_b32_e64 v88, -v88, 1.0, s[40:41]
	v_xor_b32_e32 v82, 32, v223
	v_lshlrev_b32_e32 v82, 2, v82
	ds_bpermute_b32 v83, v82, v122
	s_waitcnt lgkmcnt(0)
	v_add_f32_e32 v83, v122, v83
	v_div_scale_f32 v90, s[10:11], v83, v83, v88
	v_rcp_f32_e32 v91, v90
	s_nop 0
	v_fma_f32 v92, -v90, v91, 1.0
	v_fmac_f32_e32 v91, v92, v91
	v_div_scale_f32 v92, vcc, v88, v83, v88
	v_mul_f32_e32 v93, v92, v91
	v_fma_f32 v94, -v90, v93, v92
	v_fmac_f32_e32 v93, v94, v91
	v_fma_f32 v90, -v90, v93, v92
	s_nop 1
	v_div_fmas_f32 v90, v90, v91, v93
	v_div_fixup_f32 v96, v90, v83, v88
	v_and_b32_e32 v98, 31, v223
	v_mul_u32_u24_e32 v98, 528, v98
	v_lshrrev_b32_e32 v99, 5, v223
	v_lshl_add_u32 v98, v99, 4, v98
	s_movk_i32 s6, 0x4200
	v_mad_u32_u24 v98, v182, s6, v98
	v_pk_mul_f32 v[18:19], v[18:19], v[96:97] op_sel_hi:[1,0]
	v_pk_mul_f32 v[20:21], v[20:21], v[96:97] op_sel_hi:[1,0]
	v_pk_mul_f32 v[22:23], v[22:23], v[96:97] op_sel_hi:[1,0]
	v_pk_mul_f32 v[24:25], v[24:25], v[96:97] op_sel_hi:[1,0]
	v_pk_mul_f32 v[26:27], v[26:27], v[96:97] op_sel_hi:[1,0]
	v_pk_mul_f32 v[28:29], v[28:29], v[96:97] op_sel_hi:[1,0]
	v_pk_mul_f32 v[30:31], v[30:31], v[96:97] op_sel_hi:[1,0]
	v_pk_mul_f32 v[32:33], v[32:33], v[96:97] op_sel_hi:[1,0]
	ds_write_b128 v98, v[18:21] offset:0
	ds_write_b128 v98, v[22:25] offset:32
	ds_write_b128 v98, v[26:29] offset:64
	ds_write_b128 v98, v[30:33] offset:96
	v_pk_mul_f32 v[34:35], v[34:35], v[96:97] op_sel_hi:[1,0]
	v_pk_mul_f32 v[36:37], v[36:37], v[96:97] op_sel_hi:[1,0]
	v_pk_mul_f32 v[38:39], v[38:39], v[96:97] op_sel_hi:[1,0]
	v_pk_mul_f32 v[40:41], v[40:41], v[96:97] op_sel_hi:[1,0]
	v_pk_mul_f32 v[42:43], v[42:43], v[96:97] op_sel_hi:[1,0]
	v_pk_mul_f32 v[44:45], v[44:45], v[96:97] op_sel_hi:[1,0]
	v_pk_mul_f32 v[46:47], v[46:47], v[96:97] op_sel_hi:[1,0]
	v_pk_mul_f32 v[48:49], v[48:49], v[96:97] op_sel_hi:[1,0]
	ds_write_b128 v98, v[34:37] offset:128
	ds_write_b128 v98, v[38:41] offset:160
	ds_write_b128 v98, v[42:45] offset:192
	ds_write_b128 v98, v[46:49] offset:224
	s_waitcnt lgkmcnt(0)
	v_pk_mul_f32 v[50:51], v[50:51], v[96:97] op_sel_hi:[1,0]
	v_pk_mul_f32 v[52:53], v[52:53], v[96:97] op_sel_hi:[1,0]
	v_pk_mul_f32 v[54:55], v[54:55], v[96:97] op_sel_hi:[1,0]
	v_pk_mul_f32 v[56:57], v[56:57], v[96:97] op_sel_hi:[1,0]
	v_pk_mul_f32 v[58:59], v[58:59], v[96:97] op_sel_hi:[1,0]
	v_pk_mul_f32 v[60:61], v[60:61], v[96:97] op_sel_hi:[1,0]
	v_pk_mul_f32 v[62:63], v[62:63], v[96:97] op_sel_hi:[1,0]
	v_pk_mul_f32 v[64:65], v[64:65], v[96:97] op_sel_hi:[1,0]
	ds_write_b128 v98, v[50:53] offset:256
	ds_write_b128 v98, v[54:57] offset:288
	ds_write_b128 v98, v[58:61] offset:320
	ds_write_b128 v98, v[62:65] offset:352
	v_pk_mul_f32 v[66:67], v[66:67], v[96:97] op_sel_hi:[1,0]
	v_pk_mul_f32 v[68:69], v[68:69], v[96:97] op_sel_hi:[1,0]
	v_pk_mul_f32 v[70:71], v[70:71], v[96:97] op_sel_hi:[1,0]
	v_pk_mul_f32 v[72:73], v[72:73], v[96:97] op_sel_hi:[1,0]
	v_pk_mul_f32 v[74:75], v[74:75], v[96:97] op_sel_hi:[1,0]
	v_pk_mul_f32 v[76:77], v[76:77], v[96:97] op_sel_hi:[1,0]
	v_pk_mul_f32 v[78:79], v[78:79], v[96:97] op_sel_hi:[1,0]
	v_pk_mul_f32 v[80:81], v[80:81], v[96:97] op_sel_hi:[1,0]
	ds_write_b128 v98, v[66:69] offset:384
	ds_write_b128 v98, v[70:73] offset:416
	ds_write_b128 v98, v[74:77] offset:448
	ds_write_b128 v98, v[78:81] offset:480
	s_waitcnt lgkmcnt(0)
	s_barrier
	s_add_u32 s100, s100, s14
	s_addc_u32 s101, s101, s15
	v_lshlrev_b32_e32 v132, 4, v178
	global_load_dwordx4 v[100:103], v132, s[100:101]
	global_load_dwordx4 v[104:107], v132, s[100:101] offset:64
	global_load_dwordx4 v[108:111], v132, s[100:101] offset:128
	global_load_dwordx4 v[112:115], v132, s[100:101] offset:192
	global_load_dwordx4 v[116:119], v132, s[100:101] offset:256
	global_load_dwordx4 v[120:123], v132, s[100:101] offset:320
	global_load_dwordx4 v[124:127], v132, s[100:101] offset:384
	global_load_dwordx4 v[128:131], v132, s[100:101] offset:448
	v_lshl_add_u32 v99, v179, 4, v177
	v_mul_u32_u24_e32 v99, 528, v99
	v_lshl_add_u32 v99, v178, 4, v99
	v_mad_u32_u24 v154, v182, s6, v99
	v_xor_b32_e32 v155, 1, v182
	v_mad_u32_u24 v155, v155, s6, v99
	ds_read_b128 v[82:85], v154 offset:0
	ds_read_b128 v[156:159], v155 offset:0
	ds_read_b128 v[86:89], v154 offset:64
	ds_read_b128 v[160:163], v155 offset:64
	ds_read_b128 v[90:93], v154 offset:128
	ds_read_b128 v[164:167], v155 offset:128
	ds_read_b128 v[94:97], v154 offset:192
	ds_read_b128 v[168:171], v155 offset:192
	s_waitcnt lgkmcnt(6)
	v_add_f32_e32 v38, v82, v156
	v_add_f32_e32 v39, v83, v157
	v_add_f32_e32 v36, v84, v158
	v_add_f32_e32 v37, v85, v159
	v_mul_f32_e32 v2, v38, v38
	v_fmac_f32_e32 v2, v39, v39
	v_fmac_f32_e32 v2, v36, v36
	v_fmac_f32_e32 v2, v37, v37
	s_waitcnt lgkmcnt(4)
	v_add_f32_e32 v34, v86, v160
	v_add_f32_e32 v35, v87, v161
	v_add_f32_e32 v32, v88, v162
	v_add_f32_e32 v33, v89, v163
	v_fmac_f32_e32 v2, v34, v34
	v_fmac_f32_e32 v2, v35, v35
	v_fmac_f32_e32 v2, v32, v32
	v_fmac_f32_e32 v2, v33, v33
	s_waitcnt lgkmcnt(2)
	v_add_f32_e32 v30, v90, v164
	v_add_f32_e32 v31, v91, v165
	v_add_f32_e32 v28, v92, v166
	v_add_f32_e32 v29, v93, v167
	v_fmac_f32_e32 v2, v30, v30
	v_fmac_f32_e32 v2, v31, v31
	v_fmac_f32_e32 v2, v28, v28
	v_fmac_f32_e32 v2, v29, v29
	s_waitcnt lgkmcnt(0)
	v_add_f32_e32 v26, v94, v168
	v_add_f32_e32 v27, v95, v169
	v_add_f32_e32 v24, v96, v170
	v_add_f32_e32 v25, v97, v171
	v_fmac_f32_e32 v2, v26, v26
	v_fmac_f32_e32 v2, v27, v27
	v_fmac_f32_e32 v2, v24, v24
	v_fmac_f32_e32 v2, v25, v25
	ds_read_b128 v[82:85], v154 offset:256
	ds_read_b128 v[156:159], v155 offset:256
	ds_read_b128 v[86:89], v154 offset:320
	ds_read_b128 v[160:163], v155 offset:320
	ds_read_b128 v[90:93], v154 offset:384
	ds_read_b128 v[164:167], v155 offset:384
	ds_read_b128 v[94:97], v154 offset:448
	ds_read_b128 v[168:171], v155 offset:448
	s_waitcnt lgkmcnt(6)
	v_add_f32_e32 v22, v82, v156
	v_add_f32_e32 v23, v83, v157
	v_add_f32_e32 v20, v84, v158
	v_add_f32_e32 v21, v85, v159
	v_fmac_f32_e32 v2, v22, v22
	v_fmac_f32_e32 v2, v23, v23
	v_fmac_f32_e32 v2, v20, v20
	v_fmac_f32_e32 v2, v21, v21
	s_waitcnt lgkmcnt(4)
	v_add_f32_e32 v18, v86, v160
	v_add_f32_e32 v19, v87, v161
	v_add_f32_e32 v16, v88, v162
	v_add_f32_e32 v17, v89, v163
	v_fmac_f32_e32 v2, v18, v18
	v_fmac_f32_e32 v2, v19, v19
	v_fmac_f32_e32 v2, v16, v16
	v_fmac_f32_e32 v2, v17, v17
	s_waitcnt lgkmcnt(2)
	v_add_f32_e32 v14, v90, v164
	v_add_f32_e32 v15, v91, v165
	v_add_f32_e32 v12, v92, v166
	v_add_f32_e32 v13, v93, v167
	v_fmac_f32_e32 v2, v14, v14
	v_fmac_f32_e32 v2, v15, v15
	v_fmac_f32_e32 v2, v12, v12
	v_fmac_f32_e32 v2, v13, v13
	s_waitcnt lgkmcnt(0)
	v_add_f32_e32 v8, v94, v168
	v_add_f32_e32 v9, v95, v169
	v_add_f32_e32 v6, v96, v170
	v_add_f32_e32 v7, v97, v171
	v_fmac_f32_e32 v2, v8, v8
	v_fmac_f32_e32 v2, v9, v9
	v_fmac_f32_e32 v2, v6, v6
	v_fmac_f32_e32 v2, v7, v7
	ds_bpermute_b32 v3, v176, v2
	s_load_dwordx2 s[10:11], s[44:45], 0x80
	v_lshlrev_b32_e32 v4, 3, v178
	v_mov_b32_e32 v5, v0
	s_mov_b32 s6, 0x18a10000
	s_waitcnt lgkmcnt(0)
	v_add_f32_e32 v2, v2, v3
	ds_bpermute_b32 v1, v1, v2
	s_add_u32 s10, s10, s14
	s_addc_u32 s11, s11, s15
	s_mov_b64 s[14:15], 0x18a10000
	v_lshlrev_b32_e32 v44, 4, v178
	s_waitcnt lgkmcnt(0)
	v_add_f32_e32 v1, v2, v1
	v_fmamk_f32 v1, v1, 0x3c000000, v234
	v_cmp_gt_f32_e32 vcc, s90, v1
	v_mul_f32_e32 v2, 0x4b800000, v1
	s_nop 0
	v_cndmask_b32_e32 v1, v1, v2, vcc
	v_rsq_f32_e32 v1, v1
	s_nop 0
	v_mul_f32_e32 v2, 0x45800000, v1
	v_cndmask_b32_e32 v1, v1, v2, vcc
	v_lshlrev_b32_e32 v2, 4, v179
	v_or3_b32 v2, v2, v177, v180
	v_ashrrev_i32_e32 v3, 31, v2
	v_lshlrev_b64 v[2:3], 11, v[2:3]
	v_lshl_add_u64 v[2:3], s[42:43], 0, v[2:3]
	v_lshl_add_u64 v[2:3], v[2:3], 0, s[30:31]
	v_lshl_add_u64 v[2:3], v[2:3], 0, v[4:5]
	v_add_co_u32_e32 v40, vcc, s6, v2
	v_lshl_add_u64 v[10:11], v[2:3], 0, s[14:15]
	s_nop 0
	v_addc_co_u32_e32 v41, vcc, 0, v3, vcc
	v_mul_f32_e32 v1, v227, v1
	v_mul_f32_e32 v38, v38, v1
	v_mul_f32_e32 v36, v36, v1
	v_mul_f32_e32 v34, v34, v1
	v_mul_f32_e32 v32, v32, v1
	v_mul_f32_e32 v30, v30, v1
	v_mul_f32_e32 v28, v28, v1
	v_mul_f32_e32 v26, v26, v1
	v_mul_f32_e32 v24, v24, v1
	v_mul_f32_e32 v22, v22, v1
	v_mul_f32_e32 v20, v20, v1
	v_mul_f32_e32 v18, v18, v1
	v_mul_f32_e32 v16, v16, v1
	v_mul_f32_e32 v14, v14, v1
	v_mul_f32_e32 v12, v12, v1
	s_waitcnt vmcnt(0)
	v_readfirstlane_b32 s101, v224
	v_mov_b32_e32 v42, v146
	v_mov_b32_e32 v43, v147
	v_mov_b32_e32 v2, v100
	v_mov_b32_e32 v3, v101
	v_mov_b32_e32 v4, v102
	v_mov_b32_e32 v5, v103
	v_mul_f32_e32 v2, v2, v38
	v_lshlrev_b32_e32 v38, 16, v42
	v_mul_f32_e32 v2, v2, v38
	v_mul_f32_e32 v38, v39, v1
	v_mul_f32_e32 v4, v4, v36
	v_lshlrev_b32_e32 v36, 16, v43
	v_mul_f32_e32 v3, v3, v38
	v_and_b32_e32 v38, 0xffff0000, v42
	v_mul_f32_e32 v4, v4, v36
	v_mul_f32_e32 v36, v37, v1
	v_mul_f32_e32 v3, v3, v38
	v_mul_f32_e32 v5, v5, v36
	v_and_b32_e32 v36, 0xffff0000, v43
	v_mul_f32_e32 v5, v5, v36
	s_nop 1
	v_cvt_pk_bf16_f32 v2, v2, v3
	s_nop 1
	v_cvt_pk_bf16_f32 v3, v4, v5
	global_store_dwordx2 v[40:41], v[2:3], off
	v_mov_b32_e32 v36, v148
	v_mov_b32_e32 v37, v149
	s_nop 0
	v_mov_b32_e32 v2, v104
	v_mov_b32_e32 v3, v105
	v_mov_b32_e32 v4, v106
	v_mov_b32_e32 v5, v107
	v_mul_f32_e32 v2, v2, v34
	v_lshlrev_b32_e32 v34, 16, v36
	v_mul_f32_e32 v2, v2, v34
	v_mul_f32_e32 v34, v35, v1
	v_mul_f32_e32 v4, v4, v32
	v_lshlrev_b32_e32 v32, 16, v37
	v_mul_f32_e32 v3, v3, v34
	v_and_b32_e32 v34, 0xffff0000, v36
	v_mul_f32_e32 v4, v4, v32
	v_mul_f32_e32 v32, v33, v1
	v_mul_f32_e32 v3, v3, v34
	v_mul_f32_e32 v5, v5, v32
	v_and_b32_e32 v32, 0xffff0000, v37
	v_mul_f32_e32 v5, v5, v32
	s_nop 1
	v_cvt_pk_bf16_f32 v2, v2, v3
	s_nop 1
	v_cvt_pk_bf16_f32 v3, v4, v5
	global_store_dwordx2 v[10:11], v[2:3], off offset:32
	v_mov_b32_e32 v32, v150
	v_mov_b32_e32 v33, v151
	s_nop 0
	v_mov_b32_e32 v2, v108
	v_mov_b32_e32 v3, v109
	v_mov_b32_e32 v4, v110
	v_mov_b32_e32 v5, v111
	v_mul_f32_e32 v2, v2, v30
	v_lshlrev_b32_e32 v30, 16, v32
	v_mul_f32_e32 v2, v2, v30
	v_mul_f32_e32 v30, v31, v1
	v_mul_f32_e32 v4, v4, v28
	v_lshlrev_b32_e32 v28, 16, v33
	v_mul_f32_e32 v3, v3, v30
	v_and_b32_e32 v30, 0xffff0000, v32
	v_mul_f32_e32 v4, v4, v28
	v_mul_f32_e32 v28, v29, v1
	v_mul_f32_e32 v3, v3, v30
	v_mul_f32_e32 v5, v5, v28
	v_and_b32_e32 v28, 0xffff0000, v33
	v_mul_f32_e32 v5, v5, v28
	s_nop 1
	v_cvt_pk_bf16_f32 v2, v2, v3
	s_nop 1
	v_cvt_pk_bf16_f32 v3, v4, v5
	global_store_dwordx2 v[10:11], v[2:3], off offset:64
	v_mov_b32_e32 v28, v152
	v_mov_b32_e32 v29, v153
	s_nop 0
	v_mov_b32_e32 v2, v112
	v_mov_b32_e32 v3, v113
	v_mov_b32_e32 v4, v114
	v_mov_b32_e32 v5, v115
	v_mul_f32_e32 v2, v2, v26
	v_lshlrev_b32_e32 v26, 16, v28
	v_mul_f32_e32 v2, v2, v26
	v_mul_f32_e32 v26, v27, v1
	v_mul_f32_e32 v4, v4, v24
	v_lshlrev_b32_e32 v24, 16, v29
	v_mul_f32_e32 v3, v3, v26
	v_and_b32_e32 v26, 0xffff0000, v28
	v_mul_f32_e32 v4, v4, v24
	v_mul_f32_e32 v24, v25, v1
	v_mul_f32_e32 v3, v3, v26
	v_mul_f32_e32 v5, v5, v24
	v_and_b32_e32 v24, 0xffff0000, v29
	v_mul_f32_e32 v5, v5, v24
	s_nop 1
	v_cvt_pk_bf16_f32 v2, v2, v3
	s_nop 1
	v_cvt_pk_bf16_f32 v3, v4, v5
	global_store_dwordx2 v[10:11], v[2:3], off offset:96
	v_mov_b32_e32 v24, v188
	v_mov_b32_e32 v25, v189
	s_nop 0
	v_mov_b32_e32 v2, v116
	v_mov_b32_e32 v3, v117
	v_mov_b32_e32 v4, v118
	v_mov_b32_e32 v5, v119
	v_mul_f32_e32 v2, v2, v22
	v_lshlrev_b32_e32 v22, 16, v24
	v_mul_f32_e32 v2, v2, v22
	v_mul_f32_e32 v22, v23, v1
	v_mul_f32_e32 v4, v4, v20
	v_lshlrev_b32_e32 v20, 16, v25
	v_mul_f32_e32 v3, v3, v22
	v_and_b32_e32 v22, 0xffff0000, v24
	v_mul_f32_e32 v4, v4, v20
	v_mul_f32_e32 v20, v21, v1
	v_mul_f32_e32 v3, v3, v22
	v_mul_f32_e32 v5, v5, v20
	v_and_b32_e32 v20, 0xffff0000, v25
	v_mul_f32_e32 v5, v5, v20
	s_nop 1
	v_cvt_pk_bf16_f32 v2, v2, v3
	s_nop 1
	v_cvt_pk_bf16_f32 v3, v4, v5
	global_store_dwordx2 v[10:11], v[2:3], off offset:128
	v_mov_b32_e32 v20, v190
	v_mov_b32_e32 v21, v191
	s_nop 0
	v_mov_b32_e32 v2, v120
	v_mov_b32_e32 v3, v121
	v_mov_b32_e32 v4, v122
	v_mov_b32_e32 v5, v123
	v_mul_f32_e32 v2, v2, v18
	v_lshlrev_b32_e32 v18, 16, v20
	v_mul_f32_e32 v2, v2, v18
	v_mul_f32_e32 v18, v19, v1
	v_mul_f32_e32 v4, v4, v16
	v_lshlrev_b32_e32 v16, 16, v21
	v_mul_f32_e32 v3, v3, v18
	v_and_b32_e32 v18, 0xffff0000, v20
	v_mul_f32_e32 v4, v4, v16
	v_mul_f32_e32 v16, v17, v1
	v_mul_f32_e32 v3, v3, v18
	v_mul_f32_e32 v5, v5, v16
	v_and_b32_e32 v16, 0xffff0000, v21
	v_mul_f32_e32 v5, v5, v16
	s_nop 1
	v_cvt_pk_bf16_f32 v2, v2, v3
	s_nop 1
	v_cvt_pk_bf16_f32 v3, v4, v5
	global_store_dwordx2 v[10:11], v[2:3], off offset:160
	v_mov_b32_e32 v16, v192
	v_mov_b32_e32 v17, v193
	s_nop 0
	v_mov_b32_e32 v2, v124
	v_mov_b32_e32 v3, v125
	v_mov_b32_e32 v4, v126
	v_mov_b32_e32 v5, v127
	v_mul_f32_e32 v2, v2, v14
	v_lshlrev_b32_e32 v14, 16, v16
	v_mul_f32_e32 v2, v2, v14
	v_mul_f32_e32 v14, v15, v1
	v_mul_f32_e32 v4, v4, v12
	v_lshlrev_b32_e32 v12, 16, v17
	v_mul_f32_e32 v3, v3, v14
	v_and_b32_e32 v14, 0xffff0000, v16
	v_mul_f32_e32 v4, v4, v12
	v_mul_f32_e32 v12, v13, v1
	v_mul_f32_e32 v3, v3, v14
	v_mul_f32_e32 v5, v5, v12
	v_and_b32_e32 v12, 0xffff0000, v17
	v_mul_f32_e32 v5, v5, v12
	s_nop 1
	v_cvt_pk_bf16_f32 v2, v2, v3
	s_nop 1
	v_cvt_pk_bf16_f32 v3, v4, v5
	global_store_dwordx2 v[10:11], v[2:3], off offset:192
	v_mov_b32_e32 v2, v194
	v_mov_b32_e32 v3, v195
	s_nop 0
	v_mov_b32_e32 v12, v128
	v_mov_b32_e32 v13, v129
	v_mov_b32_e32 v14, v130
	v_mov_b32_e32 v15, v131
	v_mul_f32_e32 v4, v8, v1
	v_lshlrev_b32_e32 v5, 16, v2
	v_mul_f32_e32 v4, v4, v12
	v_mul_f32_e32 v4, v4, v5
	v_mul_f32_e32 v5, v9, v1
	v_mul_f32_e32 v5, v5, v13
	v_and_b32_e32 v2, 0xffff0000, v2
	v_mul_f32_e32 v2, v5, v2
	v_mul_f32_e32 v5, v6, v1
	v_mul_f32_e32 v1, v7, v1
	v_mul_f32_e32 v5, v5, v14
	v_lshlrev_b32_e32 v6, 16, v3
	v_mul_f32_e32 v1, v1, v15
	v_and_b32_e32 v3, 0xffff0000, v3
	v_mul_f32_e32 v5, v5, v6
	v_mul_f32_e32 v1, v1, v3
	s_nop 1
	v_cvt_pk_bf16_f32 v2, v4, v2
	s_nop 1
	v_cvt_pk_bf16_f32 v3, v5, v1
	global_store_dwordx2 v[10:11], v[2:3], off offset:224
	s_barrier
